# GEMM1 epilogue: r0 prefetch + conv weights in LDS; GEMM4b epilogue: rope cos/sin loads merged and software-pipelined
# speedup vs baseline: 1.0101x; 1.0101x over previous
.LBB0_423:
	s_cmp_lt_i32 s28, 2
	s_cselect_b64 s[0:1], -1, 0
	s_and_b64 s[14:15], s[0:1], s[6:7]
	s_andn2_b64 vcc, exec, s[14:15]
	s_cbranch_vccnz .LBB0_459
	v_mbcnt_lo_u32_b32 v240, -1, 0
	v_mbcnt_hi_u32_b32 v240, -1, v240
	v_lshlrev_b32_e32 v240, 4, v240
	s_lshl_b32 s98, s76, 10
	v_add_u32_e32 v240, s98, v240
	s_add_i32 s99, s98, 0x22000
	s_mov_b32 m0, s99
	s_nop 0
	global_load_lds_dwordx4 v240, s[44:45]
	s_cmp_lt_u32 s76, 4
	s_cbranch_scc0 .Lg1_cw_done
	v_add_u32_e32 v240, 0x2000, v240
	s_add_i32 m0, s99, 0x2000
	s_nop 0
	global_load_lds_dwordx4 v240, s[44:45]
.Lg1_cw_done:
	v_readlane_b32 s0, v247, 1
	s_cmpk_lt_i32 s2, 0x1000
	v_mbcnt_lo_u32_b32 v14, -1, 0
	v_mbcnt_hi_u32_b32 v14, -1, v14
	s_cselect_b64 s[4:5], -1, 0
	v_add_u32_e32 v0, s0, v14
	s_cmpk_gt_i32 s2, 0xfff
	v_readfirstlane_b32 s6, v0
	s_cbranch_scc1 .LBB0_426
	s_ashr_i32 s0, s2, 31
	s_lshr_b32 s0, s0, 29
	s_add_i32 s0, s2, s0
	s_and_b32 s1, s0, -8
	s_sub_i32 s1, s2, s1
	s_lshl_b32 s7, s1, 9
	s_ashr_i32 s0, s0, 3
	s_mul_i32 s3, s1, 0x201
	s_cmp_lt_i32 s1, 0
	s_cselect_b32 s1, s3, s7
	s_add_i32 s0, s1, s0
	s_ashr_i32 s1, s0, 31
	s_lshr_b32 s1, s1, 26
	s_add_i32 s1, s0, s1
	s_ashr_i32 s3, s1, 6
	s_andn2_b32 s1, s1, 63
	s_sub_i32 s0, s0, s1
	s_bfe_i32 s1, s0, 0x80000
	s_bfe_u32 s1, s1, 0x2000d
	s_add_i32 s1, s0, s1
	s_bfe_i32 s7, s1, 0x80000
	s_and_b32 s1, s1, 0xfc
	s_sub_i32 s0, s0, s1
	s_lshl_b32 s3, s3, 2
	s_sext_i32_i16 s7, s7
	s_sext_i32_i8 s0, s0
	s_add_i32 s52, s3, s0
	s_ashr_i32 s62, s7, 2

.LBB0_439:
	ds_read_b128 v[128:131], v192
	ds_read_b128 v[132:135], v192 offset:1024
	ds_read_b128 v[136:139], v192 offset:2048
	ds_read_b128 v[158:161], v192 offset:3072
	ds_read_b128 v[168:171], v193
	ds_read_b128 v[172:175], v193 offset:1024
	ds_read_b128 v[196:199], v193 offset:2048
	ds_read_b128 v[200:203], v193 offset:3072
	s_add_u32 s66, s64, 0xfffc0080
	s_addc_u32 s67, s65, -1
	s_cmp_eq_u32 s86, 12
	s_cselect_b32 s69, s53, s67
	s_cselect_b32 s68, s57, s66
	s_cselect_b32 s67, s55, s85
	s_cselect_b32 s66, s63, s84
	s_cbranch_scc0 .Lg1_nopf
	s_lshl_b32 s98, s52, 8
	v_add_u32_e32 v240, s98, v165
	v_ashrrev_i32_e32 v241, 31, v240
	v_lshl_add_u64 v[240:241], v[240:241], 2, s[20:21]
	global_load_dword v242, v[240:241], off
	global_load_dword v243, v[240:241], off offset:64
	global_load_dword v244, v[240:241], off offset:128
	global_load_dword v245, v[240:241], off offset:192
	global_load_dword v246, v[240:241], off offset:512
	global_load_dword v248, v[240:241], off offset:576
	global_load_dword v249, v[240:241], off offset:640
	global_load_dword v250, v[240:241], off offset:704
.Lg1_nopf:
	v_lshl_add_u64 v[162:163], s[64:65], 0, v[150:151]
	s_add_i32 m0, s70, 0xc000
	ds_read_b128 v[204:207], v194
	ds_read_b128 v[208:211], v194 offset:1024
	ds_read_b128 v[212:215], v194 offset:2048
	ds_read_b128 v[216:219], v194 offset:3072
	ds_read_b128 v[220:223], v194 offset:4096
	ds_read_b128 v[224:227], v194 offset:5120
	ds_read_b128 v[228:231], v194 offset:6144
	ds_read_b128 v[232:235], v194 offset:7168
	global_load_lds_dwordx4 v[162:163], off
	v_lshl_add_u64 v[162:163], s[64:65], 0, v[152:153]
	s_add_i32 m0, s70, 0xe000
	s_nop 0
	global_load_lds_dwordx4 v[162:163], off
	s_waitcnt vmcnt(8)
	s_waitcnt lgkmcnt(0)
	s_barrier
	s_setprio 1
	s_waitcnt lgkmcnt(0)
	v_mfma_f32_16x16x32_bf16 v[124:127], v[128:131], v[204:207], v[124:127]
	v_mfma_f32_16x16x32_bf16 v[120:123], v[136:139], v[204:207], v[120:123]
	v_mfma_f32_16x16x32_bf16 v[96:99], v[128:131], v[212:215], v[96:99]
	v_mfma_f32_16x16x32_bf16 v[88:91], v[136:139], v[212:215], v[88:91]
	v_mfma_f32_16x16x32_bf16 v[76:79], v[128:131], v[220:223], v[76:79]
	v_mfma_f32_16x16x32_bf16 v[72:75], v[136:139], v[220:223], v[72:75]
	v_mfma_f32_16x16x32_bf16 v[60:63], v[128:131], v[228:231], v[60:63]
	v_mfma_f32_16x16x32_bf16 v[108:111], v[136:139], v[228:231], v[108:111]
	v_mfma_f32_16x16x32_bf16 v[124:127], v[132:135], v[208:211], v[124:127]
	v_mfma_f32_16x16x32_bf16 v[120:123], v[158:161], v[208:211], v[120:123]
	v_mfma_f32_16x16x32_bf16 v[96:99], v[132:135], v[216:219], v[96:99]
	v_mfma_f32_16x16x32_bf16 v[88:91], v[158:161], v[216:219], v[88:91]
	v_mfma_f32_16x16x32_bf16 v[76:79], v[132:135], v[224:227], v[76:79]
	v_mfma_f32_16x16x32_bf16 v[72:75], v[158:161], v[224:227], v[72:75]
	v_mfma_f32_16x16x32_bf16 v[60:63], v[132:135], v[232:235], v[60:63]
	v_mfma_f32_16x16x32_bf16 v[108:111], v[158:161], v[232:235], v[108:111]
	s_setprio 0
	s_setprio 1
	v_mfma_f32_16x16x32_bf16 v[116:119], v[168:171], v[204:207], v[116:119]
	v_mfma_f32_16x16x32_bf16 v[112:115], v[196:199], v[204:207], v[112:115]
	v_mfma_f32_16x16x32_bf16 v[84:87], v[168:171], v[212:215], v[84:87]
	v_mfma_f32_16x16x32_bf16 v[80:83], v[196:199], v[212:215], v[80:83]
	v_mfma_f32_16x16x32_bf16 v[68:71], v[168:171], v[220:223], v[68:71]
	v_mfma_f32_16x16x32_bf16 v[64:67], v[196:199], v[220:223], v[64:67]
	v_mfma_f32_16x16x32_bf16 v[104:107], v[168:171], v[228:231], v[104:107]
	v_mfma_f32_16x16x32_bf16 v[56:59], v[196:199], v[228:231], v[56:59]
	v_mfma_f32_16x16x32_bf16 v[116:119], v[172:175], v[208:211], v[116:119]
	v_mfma_f32_16x16x32_bf16 v[112:115], v[200:203], v[208:211], v[112:115]
	v_mfma_f32_16x16x32_bf16 v[84:87], v[172:175], v[216:219], v[84:87]
	v_mfma_f32_16x16x32_bf16 v[80:83], v[200:203], v[216:219], v[80:83]
	v_mfma_f32_16x16x32_bf16 v[68:71], v[172:175], v[224:227], v[68:71]
	v_mfma_f32_16x16x32_bf16 v[64:67], v[200:203], v[224:227], v[64:67]
	v_mfma_f32_16x16x32_bf16 v[104:107], v[172:175], v[232:235], v[104:107]
	v_mfma_f32_16x16x32_bf16 v[56:59], v[200:203], v[232:235], v[56:59]
	s_setprio 0
	s_barrier
	s_add_i32 s87, s82, s23
	v_lshl_add_u64 v[162:163], s[66:67], 0, v[140:141]
	s_mov_b32 m0, s87
	ds_read_b128 v[204:207], v194 offset:16384
	ds_read_b128 v[208:211], v194 offset:17408
	ds_read_b128 v[212:215], v194 offset:18432
	ds_read_b128 v[216:219], v194 offset:19456
	ds_read_b128 v[220:223], v194 offset:20480
	ds_read_b128 v[224:227], v194 offset:21504
	ds_read_b128 v[228:231], v194 offset:22528
	ds_read_b128 v[232:235], v194 offset:23552
	global_load_lds_dwordx4 v[162:163], off
	s_add_i32 m0, s87, 0x2000
	s_add_u32 s88, s66, 0x40000
	v_lshl_add_u64 v[178:179], s[66:67], 0, v[142:143]
	s_addc_u32 s89, s67, 0
	s_add_i32 s87, s83, s23
	global_load_lds_dwordx4 v[178:179], off
	v_lshl_add_u64 v[184:185], s[88:89], 0, v[140:141]
	s_mov_b32 m0, s87
	v_lshl_add_u64 v[236:237], s[68:69], 0, v[142:143]
	global_load_lds_dwordx4 v[184:185], off
	v_lshl_add_u64 v[184:185], s[88:89], 0, v[142:143]
	s_add_i32 m0, s87, 0x2000
	s_nop 0
	global_load_lds_dwordx4 v[184:185], off
	v_lshl_add_u64 v[184:185], s[68:69], 0, v[140:141]
	s_mov_b32 m0, s70
	s_nop 0
	global_load_lds_dwordx4 v[184:185], off
	s_mov_b32 m0, s71
	s_nop 0
	global_load_lds_dwordx4 v[236:237], off
	s_waitcnt vmcnt(8)
	s_waitcnt lgkmcnt(0)
	s_barrier
	s_setprio 1
	s_waitcnt lgkmcnt(0)
	v_mfma_f32_16x16x32_bf16 v[52:55], v[128:131], v[204:207], v[52:55]
	v_mfma_f32_16x16x32_bf16 v[48:51], v[136:139], v[204:207], v[48:51]
	v_mfma_f32_16x16x32_bf16 v[16:19], v[128:131], v[212:215], v[16:19]
	v_mfma_f32_16x16x32_bf16 v[8:11], v[136:139], v[212:215], v[8:11]
	v_mfma_f32_16x16x32_bf16 v[28:31], v[128:131], v[220:223], v[28:31]
	v_mfma_f32_16x16x32_bf16 v[24:27], v[136:139], v[220:223], v[24:27]
	v_mfma_f32_16x16x32_bf16 v[36:39], v[128:131], v[228:231], v[36:39]
	v_mfma_f32_16x16x32_bf16 v[100:103], v[136:139], v[228:231], v[100:103]
	v_mfma_f32_16x16x32_bf16 v[52:55], v[132:135], v[208:211], v[52:55]
	v_mfma_f32_16x16x32_bf16 v[48:51], v[158:161], v[208:211], v[48:51]
	v_mfma_f32_16x16x32_bf16 v[16:19], v[132:135], v[216:219], v[16:19]
	v_mfma_f32_16x16x32_bf16 v[8:11], v[158:161], v[216:219], v[8:11]
	v_mfma_f32_16x16x32_bf16 v[28:31], v[132:135], v[224:227], v[28:31]
	v_mfma_f32_16x16x32_bf16 v[24:27], v[158:161], v[224:227], v[24:27]
	v_mfma_f32_16x16x32_bf16 v[36:39], v[132:135], v[232:235], v[36:39]
	v_mfma_f32_16x16x32_bf16 v[100:103], v[158:161], v[232:235], v[100:103]
	s_setprio 0
	s_setprio 1
	v_mfma_f32_16x16x32_bf16 v[44:47], v[168:171], v[204:207], v[44:47]
	v_mfma_f32_16x16x32_bf16 v[40:43], v[196:199], v[204:207], v[40:43]
	v_mfma_f32_16x16x32_bf16 v[0:3], v[168:171], v[212:215], v[0:3]
	v_mfma_f32_16x16x32_bf16 v[4:7], v[196:199], v[212:215], v[4:7]
	v_mfma_f32_16x16x32_bf16 v[12:15], v[168:171], v[220:223], v[12:15]
	v_mfma_f32_16x16x32_bf16 v[20:23], v[196:199], v[220:223], v[20:23]
	v_mfma_f32_16x16x32_bf16 v[92:95], v[168:171], v[228:231], v[92:95]
	v_mfma_f32_16x16x32_bf16 v[32:35], v[196:199], v[228:231], v[32:35]
	v_mfma_f32_16x16x32_bf16 v[44:47], v[172:175], v[208:211], v[44:47]
	v_mfma_f32_16x16x32_bf16 v[40:43], v[200:203], v[208:211], v[40:43]
	v_mfma_f32_16x16x32_bf16 v[0:3], v[172:175], v[216:219], v[0:3]
	v_mfma_f32_16x16x32_bf16 v[4:7], v[200:203], v[216:219], v[4:7]
	v_mfma_f32_16x16x32_bf16 v[12:15], v[172:175], v[224:227], v[12:15]
	v_mfma_f32_16x16x32_bf16 v[20:23], v[200:203], v[224:227], v[20:23]
	v_mfma_f32_16x16x32_bf16 v[92:95], v[172:175], v[232:235], v[92:95]
	v_mfma_f32_16x16x32_bf16 v[32:35], v[200:203], v[232:235], v[32:35]
	s_setprio 0
	s_barrier
	s_add_i32 s87, 0, 0x18000
	s_add_i32 s88, 0, 0x1c000
	v_add_u32_e32 v158, s87, v167
	v_add_u32_e32 v164, s88, v167
	ds_read_b128 v[128:131], v158
	ds_read_b128 v[132:135], v158 offset:1024
	ds_read_b128 v[136:139], v158 offset:2048
	ds_read_b128 v[158:161], v158 offset:3072
	ds_read_b128 v[168:171], v164
	ds_read_b128 v[172:175], v164 offset:1024
	ds_read_b128 v[196:199], v164 offset:2048
	ds_read_b128 v[200:203], v164 offset:3072
	s_add_u32 s68, s68, 0x40000
	s_addc_u32 s69, s69, 0
	s_mov_b32 m0, s72
	v_lshl_add_u64 v[238:239], s[68:69], 0, v[140:141]
	ds_read_b128 v[204:207], v194 offset:32768
	ds_read_b128 v[208:211], v194 offset:33792
	ds_read_b128 v[212:215], v194 offset:34816
	ds_read_b128 v[216:219], v194 offset:35840
	ds_read_b128 v[220:223], v194 offset:36864
	ds_read_b128 v[224:227], v194 offset:37888
	ds_read_b128 v[228:231], v194 offset:38912
	ds_read_b128 v[232:235], v194 offset:39936
	global_load_lds_dwordx4 v[238:239], off
	v_lshl_add_u64 v[238:239], s[68:69], 0, v[142:143]
	s_mov_b32 m0, s73
	s_nop 0
	global_load_lds_dwordx4 v[238:239], off
	s_waitcnt vmcnt(8)
	s_waitcnt lgkmcnt(0)
	s_barrier
	s_setprio 1
	s_waitcnt lgkmcnt(0)
	v_mfma_f32_16x16x32_bf16 v[124:127], v[128:131], v[204:207], v[124:127]
	v_mfma_f32_16x16x32_bf16 v[120:123], v[136:139], v[204:207], v[120:123]
	v_mfma_f32_16x16x32_bf16 v[96:99], v[128:131], v[212:215], v[96:99]
	v_mfma_f32_16x16x32_bf16 v[88:91], v[136:139], v[212:215], v[88:91]
	v_mfma_f32_16x16x32_bf16 v[76:79], v[128:131], v[220:223], v[76:79]
	v_mfma_f32_16x16x32_bf16 v[72:75], v[136:139], v[220:223], v[72:75]
	v_mfma_f32_16x16x32_bf16 v[60:63], v[128:131], v[228:231], v[60:63]
	v_mfma_f32_16x16x32_bf16 v[108:111], v[136:139], v[228:231], v[108:111]
	v_mfma_f32_16x16x32_bf16 v[124:127], v[132:135], v[208:211], v[124:127]
	v_mfma_f32_16x16x32_bf16 v[120:123], v[158:161], v[208:211], v[120:123]
	v_mfma_f32_16x16x32_bf16 v[96:99], v[132:135], v[216:219], v[96:99]
	v_mfma_f32_16x16x32_bf16 v[88:91], v[158:161], v[216:219], v[88:91]
	v_mfma_f32_16x16x32_bf16 v[76:79], v[132:135], v[224:227], v[76:79]
	v_mfma_f32_16x16x32_bf16 v[72:75], v[158:161], v[224:227], v[72:75]
	v_mfma_f32_16x16x32_bf16 v[60:63], v[132:135], v[232:235], v[60:63]
	v_mfma_f32_16x16x32_bf16 v[108:111], v[158:161], v[232:235], v[108:111]
	s_setprio 0
	s_setprio 1
	v_mfma_f32_16x16x32_bf16 v[116:119], v[168:171], v[204:207], v[116:119]
	v_mfma_f32_16x16x32_bf16 v[112:115], v[196:199], v[204:207], v[112:115]
	v_mfma_f32_16x16x32_bf16 v[84:87], v[168:171], v[212:215], v[84:87]
	v_mfma_f32_16x16x32_bf16 v[80:83], v[196:199], v[212:215], v[80:83]
	v_mfma_f32_16x16x32_bf16 v[68:71], v[168:171], v[220:223], v[68:71]
	v_mfma_f32_16x16x32_bf16 v[64:67], v[196:199], v[220:223], v[64:67]
	v_mfma_f32_16x16x32_bf16 v[104:107], v[168:171], v[228:231], v[104:107]
	v_mfma_f32_16x16x32_bf16 v[56:59], v[196:199], v[228:231], v[56:59]
	v_mfma_f32_16x16x32_bf16 v[116:119], v[172:175], v[208:211], v[116:119]
	v_mfma_f32_16x16x32_bf16 v[112:115], v[200:203], v[208:211], v[112:115]
	v_mfma_f32_16x16x32_bf16 v[84:87], v[172:175], v[216:219], v[84:87]
	v_mfma_f32_16x16x32_bf16 v[80:83], v[200:203], v[216:219], v[80:83]
	v_mfma_f32_16x16x32_bf16 v[68:71], v[172:175], v[224:227], v[68:71]
	v_mfma_f32_16x16x32_bf16 v[64:67], v[200:203], v[224:227], v[64:67]
	v_mfma_f32_16x16x32_bf16 v[104:107], v[172:175], v[232:235], v[104:107]
	v_mfma_f32_16x16x32_bf16 v[56:59], v[200:203], v[232:235], v[56:59]
	s_setprio 0
	s_barrier
	s_add_i32 s68, s87, s23
	v_lshl_add_u64 v[162:163], v[162:163], 0, s[36:37]
	s_mov_b32 m0, s68
	ds_read_b128 v[204:207], v194 offset:49152
	ds_read_b128 v[208:211], v194 offset:50176
	ds_read_b128 v[212:215], v194 offset:51200
	ds_read_b128 v[216:219], v194 offset:52224
	ds_read_b128 v[220:223], v194 offset:53248
	ds_read_b128 v[224:227], v194 offset:54272
	ds_read_b128 v[228:231], v194 offset:55296
	ds_read_b128 v[232:235], v194 offset:56320
	global_load_lds_dwordx4 v[162:163], off
	s_add_i32 m0, s68, 0x2000
	s_add_u32 s66, s66, 0x40080
	v_lshl_add_u64 v[162:163], v[178:179], 0, s[36:37]
	s_addc_u32 s67, s67, 0
	s_add_i32 s68, s88, s23
	global_load_lds_dwordx4 v[162:163], off
	v_lshl_add_u64 v[162:163], s[66:67], 0, v[140:141]
	s_mov_b32 m0, s68
	s_nop 0
	global_load_lds_dwordx4 v[162:163], off
	v_lshl_add_u64 v[162:163], s[66:67], 0, v[142:143]
	s_add_i32 m0, s68, 0x2000
	s_nop 0
	global_load_lds_dwordx4 v[162:163], off
	v_lshl_add_u64 v[162:163], v[184:185], 0, s[36:37]
	s_mov_b32 m0, s80
	s_nop 0
	global_load_lds_dwordx4 v[162:163], off
	v_lshl_add_u64 v[162:163], v[236:237], 0, s[36:37]
	s_mov_b32 m0, s81
	s_nop 0
	global_load_lds_dwordx4 v[162:163], off
	s_waitcnt vmcnt(8)
	s_waitcnt lgkmcnt(0)
	s_barrier
	s_setprio 1
	s_waitcnt lgkmcnt(0)
	v_mfma_f32_16x16x32_bf16 v[52:55], v[128:131], v[204:207], v[52:55]
	v_mfma_f32_16x16x32_bf16 v[48:51], v[136:139], v[204:207], v[48:51]
	v_mfma_f32_16x16x32_bf16 v[16:19], v[128:131], v[212:215], v[16:19]
	v_mfma_f32_16x16x32_bf16 v[8:11], v[136:139], v[212:215], v[8:11]
	v_mfma_f32_16x16x32_bf16 v[28:31], v[128:131], v[220:223], v[28:31]
	v_mfma_f32_16x16x32_bf16 v[24:27], v[136:139], v[220:223], v[24:27]
	v_mfma_f32_16x16x32_bf16 v[36:39], v[128:131], v[228:231], v[36:39]
	v_mfma_f32_16x16x32_bf16 v[100:103], v[136:139], v[228:231], v[100:103]
	v_mfma_f32_16x16x32_bf16 v[52:55], v[132:135], v[208:211], v[52:55]
	v_mfma_f32_16x16x32_bf16 v[48:51], v[158:161], v[208:211], v[48:51]
	v_mfma_f32_16x16x32_bf16 v[16:19], v[132:135], v[216:219], v[16:19]
	v_mfma_f32_16x16x32_bf16 v[8:11], v[158:161], v[216:219], v[8:11]
	v_mfma_f32_16x16x32_bf16 v[28:31], v[132:135], v[224:227], v[28:31]
	v_mfma_f32_16x16x32_bf16 v[24:27], v[158:161], v[224:227], v[24:27]
	v_mfma_f32_16x16x32_bf16 v[36:39], v[132:135], v[232:235], v[36:39]
	v_mfma_f32_16x16x32_bf16 v[100:103], v[158:161], v[232:235], v[100:103]
	s_setprio 0
	s_setprio 1
	v_mfma_f32_16x16x32_bf16 v[44:47], v[168:171], v[204:207], v[44:47]
	v_mfma_f32_16x16x32_bf16 v[40:43], v[196:199], v[204:207], v[40:43]
	v_mfma_f32_16x16x32_bf16 v[0:3], v[168:171], v[212:215], v[0:3]
	v_mfma_f32_16x16x32_bf16 v[4:7], v[196:199], v[212:215], v[4:7]
	v_mfma_f32_16x16x32_bf16 v[12:15], v[168:171], v[220:223], v[12:15]
	v_mfma_f32_16x16x32_bf16 v[20:23], v[196:199], v[220:223], v[20:23]
	v_mfma_f32_16x16x32_bf16 v[92:95], v[168:171], v[228:231], v[92:95]
	v_mfma_f32_16x16x32_bf16 v[32:35], v[196:199], v[228:231], v[32:35]
	v_mfma_f32_16x16x32_bf16 v[44:47], v[172:175], v[208:211], v[44:47]
	v_mfma_f32_16x16x32_bf16 v[40:43], v[200:203], v[208:211], v[40:43]
	v_mfma_f32_16x16x32_bf16 v[0:3], v[172:175], v[216:219], v[0:3]
	v_mfma_f32_16x16x32_bf16 v[4:7], v[200:203], v[216:219], v[4:7]
	v_mfma_f32_16x16x32_bf16 v[12:15], v[172:175], v[224:227], v[12:15]
	v_mfma_f32_16x16x32_bf16 v[20:23], v[200:203], v[224:227], v[20:23]
	v_mfma_f32_16x16x32_bf16 v[92:95], v[172:175], v[232:235], v[92:95]
	v_mfma_f32_16x16x32_bf16 v[32:35], v[200:203], v[232:235], v[32:35]
	s_setprio 0
	s_barrier
	s_add_i32 s86, s86, 2
	s_add_u32 s64, s64, 0x100
	s_addc_u32 s65, s65, 0
	s_add_u32 s84, s84, 0x100
	s_addc_u32 s85, s85, 0
	s_cmp_gt_u32 s86, 13
	s_cbranch_scc0 .LBB0_439
	s_and_b64 vcc, exec, s[38:39]
	s_cbranch_vccz .LBB0_442
	s_barrier
.LBB0_442:
	s_lshl_b32 s55, s52, 8
	v_add_u32_e32 v184, s55, v165
	v_mbcnt_lo_u32_b32 v128, -1, 0
	v_mbcnt_hi_u32_b32 v128, -1, v128
	v_ashrrev_i32_e32 v185, 31, v184
	v_lshl_add_u64 v[128:129], v[184:185], 2, s[20:21]
	v_add_u32_e32 v158, 0xb0, v184
	v_add_u32_e32 v170, 0x80, v184
	v_add_u32_e32 v162, 0x90, v184
	v_add_u32_e32 v160, 0xa0, v184
	v_ashrrev_i32_e32 v159, 31, v158
	v_ashrrev_i32_e32 v171, 31, v170
	v_ashrrev_i32_e32 v163, 31, v162
	v_ashrrev_i32_e32 v161, 31, v160
	v_lshl_add_u64 v[136:137], v[158:159], 2, s[20:21]
	v_lshl_add_u64 v[130:131], v[170:171], 2, s[20:21]
	v_lshl_add_u64 v[132:133], v[162:163], 2, s[20:21]
	v_lshl_add_u64 v[134:135], v[160:161], 2, s[20:21]
	s_waitcnt vmcnt(16)
	v_mov_b32_e32 v178, v245
	v_mov_b32_e32 v168, v250
	v_mov_b32_e32 v186, v242
	v_mov_b32_e32 v182, v243
	v_mov_b32_e32 v180, v244
	v_mov_b32_e32 v176, v246
	v_mov_b32_e32 v164, v248
	v_mov_b32_e32 v166, v249
	v_pk_mul_f32 v[108:109], v[108:109], v[178:179] op_sel_hi:[1,0]
	v_pk_mul_f32 v[110:111], v[110:111], v[178:179] op_sel_hi:[1,0]
	v_pk_mul_f32 v[104:105], v[104:105], v[178:179] op_sel_hi:[1,0]
	v_pk_mul_f32 v[106:107], v[106:107], v[178:179] op_sel_hi:[1,0]
	v_pk_mul_f32 v[128:129], v[108:109], v[104:105]
	v_pk_mul_f32 v[130:131], v[110:111], v[106:107]
	v_pk_mul_f32 v[100:101], v[100:101], v[168:169] op_sel_hi:[1,0]
	v_pk_mul_f32 v[102:103], v[102:103], v[168:169] op_sel_hi:[1,0]
	v_pk_mul_f32 v[92:93], v[92:93], v[168:169] op_sel_hi:[1,0]
	v_pk_mul_f32 v[94:95], v[94:95], v[168:169] op_sel_hi:[1,0]
	v_pk_mul_f32 v[92:93], v[100:101], v[92:93]
	v_pk_mul_f32 v[94:95], v[102:103], v[94:95]
	s_and_saveexec_b64 s[64:65], s[4:5]
	s_cbranch_execz .LBB0_444
	ds_write_b128 v195, v[128:131]
	ds_write_b128 v195, v[92:95] offset:1024

.LBB0_446:
	s_or_b64 exec, exec, s[62:63]
	v_lshlrev_b64 v[174:175], 2, v[172:173]
	s_waitcnt lgkmcnt(0)
	s_barrier
	v_add_u32_e32 v100, 0x22000, v174
	ds_read_b128 v[108:111], v100
	ds_read_b128 v[104:107], v100 offset:4096
	ds_read_b128 v[100:103], v100 offset:8192
	s_andn2_b64 vcc, exec, s[42:43]
	s_cbranch_vccnz .LBB0_448
	ds_read_b128 v[136:139], v189
	ds_read_b128 v[132:135], v188
	s_branch .LBB0_449

.LBB0_449:
	v_pk_mul_f32 v[112:113], v[112:113], v[186:187] op_sel_hi:[1,0]
	v_pk_mul_f32 v[114:115], v[114:115], v[186:187] op_sel_hi:[1,0]
	v_mul_f32_e32 v169, 0xbfb8aa3b, v112
	v_exp_f32_e32 v169, v169
	v_mul_f32_e32 v179, 0xbfb8aa3b, v114
	v_pk_mul_f32 v[126:127], v[126:127], v[186:187] op_sel_hi:[1,0]
	v_pk_mul_f32 v[124:125], v[124:125], v[186:187] op_sel_hi:[1,0]
	v_add_f32_e32 v169, 1.0, v169
	v_pk_mul_f32 v[122:123], v[122:123], v[186:187] op_sel_hi:[1,0]
	v_pk_mul_f32 v[120:121], v[120:121], v[186:187] op_sel_hi:[1,0]
	v_pk_mul_f32 v[118:119], v[118:119], v[186:187] op_sel_hi:[1,0]
	v_pk_mul_f32 v[116:117], v[116:117], v[186:187] op_sel_hi:[1,0]
	v_rcp_f32_e32 v196, v169
	v_mul_f32_e32 v169, 0xbfb8aa3b, v113
	v_exp_f32_e32 v179, v179
	v_mul_f32_e32 v186, 0xbfb8aa3b, v115
	v_exp_f32_e32 v169, v169
	v_exp_f32_e32 v186, v186
	v_add_f32_e32 v179, 1.0, v179
	v_rcp_f32_e32 v198, v179
	v_add_f32_e32 v169, 1.0, v169
	v_add_f32_e32 v179, 1.0, v186
	v_rcp_f32_e32 v199, v179
	v_rcp_f32_e32 v197, v169
	v_pk_mul_f32 v[118:119], v[122:123], v[118:119]
	v_pk_mul_f32 v[116:117], v[120:121], v[116:117]
	v_pk_mul_f32 v[114:115], v[114:115], v[198:199]
	v_pk_mul_f32 v[112:113], v[112:113], v[196:197]
	v_pk_mul_f32 v[114:115], v[126:127], v[114:115]
	v_pk_mul_f32 v[112:113], v[124:125], v[112:113]
	v_mov_b32_e32 v125, 0
	v_mov_b32_e32 v127, 0
	s_waitcnt lgkmcnt(0)
	v_cndmask_b32_e64 v138, v134, v138, s[6:7]
	v_cndmask_b32_e64 v139, v135, v139, s[6:7]
	v_mov_b32_e32 v121, 0
	v_mov_b32_e32 v123, 0
	v_mov_b32_e32 v124, 0
	v_mov_b32_dpp v125, v118 row_ror:2 row_mask:0xf bank_mask:0xf
	v_mov_b32_e32 v126, 0
	v_mov_b32_dpp v127, v119 row_ror:2 row_mask:0xf bank_mask:0xf
	v_cndmask_b32_e64 v136, v132, v136, s[6:7]
	v_cndmask_b32_e64 v137, v133, v137, s[6:7]
	v_mov_b32_e32 v120, 0
	v_mov_b32_dpp v121, v116 row_ror:2 row_mask:0xf bank_mask:0xf
	v_mov_b32_e32 v122, 0
	v_mov_b32_dpp v123, v117 row_ror:2 row_mask:0xf bank_mask:0xf
	v_mov_b32_dpp v124, v118 row_ror:1 row_mask:0xf bank_mask:0xf
	v_mov_b32_dpp v126, v119 row_ror:1 row_mask:0xf bank_mask:0xf
	v_cndmask_b32_e64 v138, v138, v125, s[8:9]
	v_cndmask_b32_e64 v139, v139, v127, s[8:9]
	v_mov_b32_dpp v120, v116 row_ror:1 row_mask:0xf bank_mask:0xf
	v_mov_b32_dpp v122, v117 row_ror:1 row_mask:0xf bank_mask:0xf
	v_cndmask_b32_e64 v136, v136, v121, s[8:9]
	v_cndmask_b32_e64 v137, v137, v123, s[8:9]
	v_cndmask_b32_e64 v134, v124, v134, s[6:7]
	v_cndmask_b32_e64 v135, v126, v135, s[6:7]
	v_pk_mul_f32 v[138:139], v[110:111], v[138:139]
	v_cndmask_b32_e64 v132, v120, v132, s[6:7]
	v_cndmask_b32_e64 v133, v122, v133, s[6:7]
	v_pk_mul_f32 v[136:137], v[108:109], v[136:137]
	v_pk_fma_f32 v[134:135], v[106:107], v[134:135], v[138:139]
	v_pk_fma_f32 v[132:133], v[104:105], v[132:133], v[136:137]
	v_pk_fma_f32 v[118:119], v[118:119], v[102:103], v[134:135]
	v_lshlrev_b64 v[134:135], 11, v[184:185]
	v_pk_fma_f32 v[116:117], v[116:117], v[100:101], v[132:133]
	v_lshl_add_u64 v[134:135], s[18:19], 0, v[134:135]
	v_pk_mul_f32 v[118:119], v[114:115], v[118:119]
	v_pk_mul_f32 v[116:117], v[112:113], v[116:117]
	v_lshl_add_u64 v[134:135], v[172:173], 1, v[134:135]
	v_cvt_pk_bf16_f32 v132, v116, v117
	v_cvt_pk_bf16_f32 v133, v118, v119
	global_store_dwordx2 v[134:135], v[132:133], off
	s_and_saveexec_b64 s[62:63], s[46:47]
	s_cbranch_execz .LBB0_451
	s_ashr_i32 s53, s52, 31
	s_lshl_b64 s[64:65], s[52:53], 13
	v_lshl_add_u64 v[132:133], v[146:147], 0, s[64:65]
	v_lshl_add_u64 v[132:133], v[132:133], 0, v[174:175]
	global_store_dwordx4 v[132:133], v[112:115], off
	v_lshl_add_u64 v[132:133], v[148:149], 0, s[64:65]
	v_lshl_add_u64 v[132:133], v[132:133], 0, v[174:175]
	global_store_dwordx4 v[132:133], v[116:119], off

.LBB0_774:
	s_lshl_b32 s40, s80, 8
	s_add_i32 s40, s40, s50
	v_or_b32_e32 v172, s40, v206
	v_ashrrev_i32_e32 v173, 31, v172
	v_lshlrev_b64 v[84:85], 5, v[172:173]
	v_or_b32_e32 v196, 16, v172
	v_lshl_add_u64 v[84:85], s[16:17], 0, v[84:85]
	v_ashrrev_i32_e32 v197, 31, v196
	v_mbcnt_lo_u32_b32 v160, -1, 0
	v_mbcnt_hi_u32_b32 v160, -1, v160
	global_load_dwordx2 v[214:215], v[84:85], off offset:16
	global_load_dwordx4 v[202:205], v[84:85], off
	v_lshlrev_b64 v[84:85], 5, v[196:197]
	v_or_b32_e32 v192, 32, v172
	v_lshl_add_u64 v[84:85], s[16:17], 0, v[84:85]
	v_ashrrev_i32_e32 v193, 31, v192
	global_load_dwordx2 v[198:199], v[84:85], off offset:16
	global_load_dwordx4 v[152:155], v[84:85], off
	v_lshlrev_b64 v[84:85], 5, v[192:193]
	v_or_b32_e32 v188, 48, v172
	v_lshl_add_u64 v[84:85], s[16:17], 0, v[84:85]
	v_ashrrev_i32_e32 v189, 31, v188
	global_load_dwordx2 v[194:195], v[84:85], off offset:16
	global_load_dwordx4 v[148:151], v[84:85], off
	v_lshlrev_b64 v[84:85], 5, v[188:189]
	v_add_u32_e32 v184, 0x80, v172
	v_lshl_add_u64 v[84:85], s[16:17], 0, v[84:85]
	v_ashrrev_i32_e32 v185, 31, v184
	global_load_dwordx2 v[190:191], v[84:85], off offset:16
	global_load_dwordx4 v[144:147], v[84:85], off
	v_lshlrev_b64 v[84:85], 5, v[184:185]
	v_add_u32_e32 v180, 0x90, v172
	v_lshl_add_u64 v[84:85], s[16:17], 0, v[84:85]
	v_ashrrev_i32_e32 v181, 31, v180
	global_load_dwordx2 v[186:187], v[84:85], off offset:16
	global_load_dwordx4 v[140:143], v[84:85], off
	v_lshlrev_b64 v[84:85], 5, v[180:181]
	v_add_u32_e32 v176, 0xa0, v172
	v_lshl_add_u64 v[84:85], s[16:17], 0, v[84:85]
	v_ashrrev_i32_e32 v177, 31, v176
	global_load_dwordx2 v[182:183], v[84:85], off offset:16
	global_load_dwordx4 v[120:123], v[84:85], off
	v_lshlrev_b64 v[84:85], 5, v[176:177]
	v_add_u32_e32 v170, 0xb0, v172
	v_lshl_add_u64 v[84:85], s[16:17], 0, v[84:85]
	v_ashrrev_i32_e32 v171, 31, v170
	global_load_dwordx2 v[178:179], v[84:85], off offset:16
	global_load_dwordx4 v[100:103], v[84:85], off
	v_lshlrev_b64 v[84:85], 5, v[170:171]
	v_lshl_add_u64 v[84:85], s[16:17], 0, v[84:85]
	global_load_dwordx2 v[174:175], v[84:85], off offset:16
	s_nop 0
	global_load_dwordx4 v[84:87], v[84:85], off
	s_lshl_b32 s8, s79, 8
	v_ashrrev_i32_e32 v200, 1, v160
	s_or_b32 s6, s8, s53
	v_and_b32_e32 v200, -8, v200
	v_add_u32_e32 v213, s6, v200
	v_mul_hi_i32 v200, v213, s60
	v_lshlrev_b64 v[172:173], 7, v[172:173]
	v_lshrrev_b32_e32 v216, 31, v200
	v_lshrrev_b32_e32 v217, 4, v200
	v_lshl_add_u64 v[200:201], s[18:19], 0, v[172:173]
	v_add_u32_e32 v172, v217, v216
	v_mul_lo_u32 v216, v172, s58
	v_sub_u32_e32 v254, v213, v216
	v_subrev_u32_e32 v254, 32, v254
	v_cmp_lt_i32_e64 s[98:99], -1, v254
	v_and_b32_e32 v254, 31, v254
	v_lshrrev_b32_e32 v254, 1, v254
	v_mov_b32_e32 v255, 0
	v_lshl_add_u64 v[252:253], v[254:255], 2, v[200:201]
	s_mov_b32 s101, 0
	s_nop 1
	s_mov_b64 exec, s[98:99]
	s_cbranch_execz .Lq_pf_skip_pro
	global_load_dwordx4 v[224:227], v[252:253], off offset:64
	global_load_dwordx4 v[228:231], v[252:253], off
	s_movk_i32 s100, 0x800
	v_lshl_add_u64 v[254:255], v[252:253], 0, s[100:101]
	global_load_dwordx4 v[232:235], v[254:255], off offset:64
	global_load_dwordx4 v[236:239], v[254:255], off
	s_movk_i32 s100, 0x1000
	v_lshl_add_u64 v[254:255], v[252:253], 0, s[100:101]
	global_load_dwordx4 v[240:243], v[254:255], off offset:64
	global_load_dwordx4 v[248:251], v[254:255], off
.Lq_pf_skip_pro:
	s_mov_b64 exec, -1
	s_waitcnt vmcnt(0)
	v_mov_b32_e32 v173, v214
	v_add_f32_e32 v172, v202, v203
	v_add_f32_e32 v202, v204, v205
	v_mov_b32_e32 v203, v215
	v_pk_add_f32 v[172:173], v[172:173], v[202:203]
	s_nop 0
	v_add_f32_e32 v172, v172, v173
	v_fmamk_f32 v172, v172, 0x3b2aaaab, v211
	v_rsq_f32_e32 v172, v172
	v_sub_u32_e32 v173, v213, v216
	v_cmp_lt_i32_e32 vcc, 63, v173
	v_subrev_u32_e32 v173, 64, v173
	v_mul_f32_e32 v202, 0x3e16c740, v172
	v_pk_mul_f32 v[138:139], v[138:139], v[202:203] op_sel_hi:[1,0]
	v_pk_mul_f32 v[136:137], v[136:137], v[202:203] op_sel_hi:[1,0]
	v_pk_mul_f32 v[204:205], v[134:135], v[202:203] op_sel_hi:[1,0]
	v_pk_mul_f32 v[134:135], v[132:133], v[202:203] op_sel_hi:[1,0]
	v_lshrrev_b32_e32 v172, 1, v173
	s_and_saveexec_b64 s[6:7], vcc
	s_cbranch_execz .LBB0_776
	s_waitcnt vmcnt(8)
	v_pk_mul_f32 v[132:133], v[204:205], v[226:227]
	v_pk_mul_f32 v[222:223], v[134:135], v[224:225]
	v_pk_mul_f32 v[226:227], v[138:139], v[226:227]
	v_pk_mul_f32 v[224:225], v[136:137], v[224:225]
	v_pk_fma_f32 v[138:139], v[138:139], v[230:231], v[132:133] neg_lo:[0,0,1] neg_hi:[0,0,1]
	v_pk_fma_f32 v[136:137], v[136:137], v[228:229], v[222:223] neg_lo:[0,0,1] neg_hi:[0,0,1]
	v_pk_fma_f32 v[204:205], v[204:205], v[230:231], v[226:227]
	v_pk_fma_f32 v[134:135], v[134:135], v[228:229], v[224:225]
.LBB0_776:
	s_or_b64 exec, exec, s[6:7]
	v_cvt_pk_bf16_f32 v132, v136, v137
	v_add_u32_e32 v136, 32, v213
	v_mul_hi_i32 v137, v136, s60
	v_cvt_pk_bf16_f32 v133, v138, v139
	v_lshrrev_b32_e32 v138, 31, v137
	v_lshrrev_b32_e32 v137, 4, v137
	v_add_u32_e32 v137, v137, v138
	v_mul_lo_u32 v137, v137, s58
	v_mov_b32_e32 v203, v202
	v_sub_u32_e32 v173, v136, v137
	v_mov_b32_e32 v136, v202
	v_mov_b32_e32 v137, v202
	v_pk_mul_f32 v[138:139], v[124:125], v[202:203]
	v_subrev_u32_e32 v124, 64, v173
	v_pk_mul_f32 v[130:131], v[130:131], v[136:137]
	v_pk_mul_f32 v[128:129], v[128:129], v[202:203]
	v_pk_mul_f32 v[126:127], v[126:127], v[136:137]
	v_cmp_lt_i32_e64 s[6:7], 63, v173
	v_lshrrev_b32_e32 v124, 1, v124
	v_cvt_pk_bf16_f32 v134, v134, v135
	v_cvt_pk_bf16_f32 v135, v204, v205
	s_and_saveexec_b64 s[38:39], s[6:7]
	s_cbranch_execz .LBB0_778
	s_waitcnt vmcnt(8)
	v_pk_mul_f32 v[136:137], v[126:127], v[226:227]
	v_pk_mul_f32 v[204:205], v[138:139], v[224:225]
	v_pk_mul_f32 v[226:227], v[130:131], v[226:227]
	v_pk_mul_f32 v[224:225], v[128:129], v[224:225]
	v_pk_fma_f32 v[130:131], v[130:131], v[230:231], v[136:137] neg_lo:[0,0,1] neg_hi:[0,0,1]
	v_pk_fma_f32 v[128:129], v[128:129], v[228:229], v[204:205] neg_lo:[0,0,1] neg_hi:[0,0,1]
	v_pk_fma_f32 v[126:127], v[126:127], v[230:231], v[226:227]
	v_pk_fma_f32 v[138:139], v[138:139], v[228:229], v[224:225]
.LBB0_778:
	s_or_b64 exec, exec, s[38:39]
	s_movk_i32 s100, 0x1800
	v_lshl_add_u64 v[254:255], v[252:253], 0, s[100:101]
	s_mov_b64 exec, s[98:99]
	s_cbranch_execz .Lq_pf_skip0
	global_load_dwordx4 v[224:227], v[254:255], off offset:64
	global_load_dwordx4 v[228:231], v[254:255], off
.Lq_pf_skip0:
	s_mov_b64 exec, -1
	v_add_f32_e32 v125, v152, v153
	v_add_f32_e32 v136, v154, v155
	v_add_f32_e32 v125, v125, v136
	v_add_f32_e32 v136, v198, v199
	v_add_f32_e32 v125, v125, v136
	v_fmamk_f32 v125, v125, 0x3b2aaaab, v211
	v_rsq_f32_e32 v125, v125
	v_ashrrev_i32_e32 v137, 3, v160
	s_ashr_i32 s9, s8, 31
	s_lshl_b64 s[8:9], s[8:9], 1
	v_mul_f32_e32 v136, 0x3e16c740, v125
	v_lshlrev_b32_e32 v125, 4, v160
	v_and_b32_e32 v160, 0x70, v125
	v_mul_lo_u32 v125, v137, s57
	v_add_u32_e32 v125, s56, v125
	v_cvt_pk_bf16_f32 v128, v128, v129
	v_cvt_pk_bf16_f32 v129, v130, v131
	v_cvt_pk_bf16_f32 v130, v138, v139
	v_cvt_pk_bf16_f32 v131, v126, v127
	ds_write_b128 v212, v[132:135]
	ds_write_b128 v212, v[128:131] offset:64
	s_add_u32 s8, s54, s8
	v_add_u32_e32 v132, v125, v160
	s_addc_u32 s9, s55, s9
	ds_read_b128 v[128:131], v132
	v_add_u32_e32 v154, s40, v137
	v_lshl_add_u64 v[152:153], s[8:9], 0, v[160:161]
	v_mad_i64_i32 v[126:127], s[8:9], v154, s64, v[152:153]
	ds_read_b128 v[152:155], v132 offset:1152
	s_waitcnt lgkmcnt(1)
	global_store_dwordx4 v[126:127], v[128:131], off
	v_pk_mul_f32 v[118:119], v[118:119], v[136:137] op_sel_hi:[1,0]
	v_pk_mul_f32 v[116:117], v[116:117], v[136:137] op_sel_hi:[1,0]
	v_add_co_u32_e64 v128, s[8:9], s65, v126
	v_pk_mul_f32 v[130:131], v[114:115], v[136:137] op_sel_hi:[1,0]
	s_nop 0
	v_addc_co_u32_e64 v129, s[8:9], 0, v127, s[8:9]
	s_waitcnt lgkmcnt(0)
	global_store_dwordx4 v[128:129], v[152:155], off
	v_lshlrev_b64 v[128:129], 7, v[196:197]
	v_pk_mul_f32 v[114:115], v[112:113], v[136:137] op_sel_hi:[1,0]
	v_lshl_add_u64 v[128:129], s[18:19], 0, v[128:129]
	s_and_saveexec_b64 s[8:9], vcc
	s_cbranch_execz .LBB0_780
	s_waitcnt vmcnt(8)
	v_pk_mul_f32 v[112:113], v[130:131], v[234:235]
	v_pk_mul_f32 v[134:135], v[114:115], v[232:233]
	v_pk_mul_f32 v[138:139], v[118:119], v[234:235]
	v_pk_mul_f32 v[232:233], v[116:117], v[232:233]
	v_pk_fma_f32 v[118:119], v[118:119], v[238:239], v[112:113] neg_lo:[0,0,1] neg_hi:[0,0,1]
	v_pk_fma_f32 v[116:117], v[116:117], v[236:237], v[134:135] neg_lo:[0,0,1] neg_hi:[0,0,1]
	v_pk_fma_f32 v[130:131], v[130:131], v[238:239], v[138:139]
	v_pk_fma_f32 v[114:115], v[114:115], v[236:237], v[232:233]
.LBB0_780:
	s_or_b64 exec, exec, s[8:9]
	v_mov_b32_e32 v137, v136
	v_cvt_pk_bf16_f32 v112, v116, v117
	v_mov_b32_e32 v116, v136
	v_mov_b32_e32 v117, v136
	v_pk_mul_f32 v[110:111], v[110:111], v[116:117]
	v_pk_mul_f32 v[108:109], v[108:109], v[136:137]
	v_pk_mul_f32 v[106:107], v[106:107], v[116:117]
	v_pk_mul_f32 v[116:117], v[104:105], v[136:137]
	v_cvt_pk_bf16_f32 v113, v118, v119
	v_cvt_pk_bf16_f32 v114, v114, v115
	v_cvt_pk_bf16_f32 v115, v130, v131
	s_and_saveexec_b64 s[8:9], s[6:7]
	s_cbranch_execz .LBB0_782
	s_waitcnt vmcnt(8)
	v_pk_mul_f32 v[104:105], v[106:107], v[234:235]
	v_pk_mul_f32 v[118:119], v[116:117], v[232:233]
	v_pk_mul_f32 v[234:235], v[110:111], v[234:235]
	v_pk_mul_f32 v[232:233], v[108:109], v[232:233]
	v_pk_fma_f32 v[110:111], v[110:111], v[238:239], v[104:105] neg_lo:[0,0,1] neg_hi:[0,0,1]
	v_pk_fma_f32 v[108:109], v[108:109], v[236:237], v[118:119] neg_lo:[0,0,1] neg_hi:[0,0,1]
	v_pk_fma_f32 v[106:107], v[106:107], v[238:239], v[234:235]
	v_pk_fma_f32 v[116:117], v[116:117], v[236:237], v[232:233]
.LBB0_782:
	s_or_b64 exec, exec, s[8:9]
	s_movk_i32 s100, 0x4000
	v_lshl_add_u64 v[254:255], v[252:253], 0, s[100:101]
	s_mov_b64 exec, s[98:99]
	s_cbranch_execz .Lq_pf_skip1
	global_load_dwordx4 v[232:235], v[254:255], off offset:64
	global_load_dwordx4 v[236:239], v[254:255], off
.Lq_pf_skip1:
	s_mov_b64 exec, -1
	v_add_f32_e32 v104, v148, v149
	v_add_f32_e32 v105, v150, v151
	v_cvt_pk_bf16_f32 v108, v108, v109
	v_cvt_pk_bf16_f32 v109, v110, v111
	v_cvt_pk_bf16_f32 v110, v116, v117
	v_cvt_pk_bf16_f32 v111, v106, v107
	ds_write_b128 v212, v[112:115]
	ds_write_b128 v212, v[108:111] offset:64
	v_add_f32_e32 v104, v104, v105
	v_add_f32_e32 v105, v194, v195
	v_add_f32_e32 v104, v104, v105
	ds_read_b128 v[106:109], v132
	ds_read_b128 v[110:113], v132 offset:1152
	v_fmamk_f32 v104, v104, 0x3b2aaaab, v211
	v_rsq_f32_e32 v104, v104
	v_add_co_u32_e64 v114, s[8:9], s49, v126
	v_mul_f32_e32 v104, 0x3e16c740, v104
	s_nop 0
	v_addc_co_u32_e64 v115, s[8:9], 0, v127, s[8:9]
	s_waitcnt lgkmcnt(1)
	global_store_dwordx4 v[114:115], v[106:109], off
	v_pk_mul_f32 v[98:99], v[98:99], v[104:105] op_sel_hi:[1,0]
	v_pk_mul_f32 v[96:97], v[96:97], v[104:105] op_sel_hi:[1,0]
	v_add_co_u32_e64 v106, s[8:9], s66, v126
	v_pk_mul_f32 v[108:109], v[94:95], v[104:105] op_sel_hi:[1,0]
	s_nop 0
	v_addc_co_u32_e64 v107, s[8:9], 0, v127, s[8:9]
	s_waitcnt lgkmcnt(0)
	global_store_dwordx4 v[106:107], v[110:113], off
	v_lshlrev_b64 v[106:107], 7, v[192:193]
	v_pk_mul_f32 v[94:95], v[92:93], v[104:105] op_sel_hi:[1,0]
	v_lshl_add_u64 v[106:107], s[18:19], 0, v[106:107]
	s_and_saveexec_b64 s[8:9], vcc
	s_cbranch_execz .LBB0_784
	s_waitcnt vmcnt(8)
	v_pk_mul_f32 v[92:93], v[108:109], v[242:243]
	v_pk_mul_f32 v[118:119], v[94:95], v[240:241]
	v_pk_mul_f32 v[242:243], v[98:99], v[242:243]
	v_pk_mul_f32 v[240:241], v[96:97], v[240:241]
	v_pk_fma_f32 v[98:99], v[98:99], v[250:251], v[92:93] neg_lo:[0,0,1] neg_hi:[0,0,1]
	v_pk_fma_f32 v[96:97], v[96:97], v[248:249], v[118:119] neg_lo:[0,0,1] neg_hi:[0,0,1]
	v_pk_fma_f32 v[108:109], v[108:109], v[250:251], v[242:243]
	v_pk_fma_f32 v[94:95], v[94:95], v[248:249], v[240:241]
.LBB0_784:
	s_or_b64 exec, exec, s[8:9]
	v_mov_b32_e32 v105, v104
	v_cvt_pk_bf16_f32 v92, v96, v97
	v_mov_b32_e32 v96, v104
	v_mov_b32_e32 v97, v104
	v_pk_mul_f32 v[90:91], v[90:91], v[96:97]
	v_pk_mul_f32 v[88:89], v[88:89], v[104:105]
	v_pk_mul_f32 v[82:83], v[82:83], v[96:97]
	v_pk_mul_f32 v[96:97], v[80:81], v[104:105]
	v_cvt_pk_bf16_f32 v93, v98, v99
	v_cvt_pk_bf16_f32 v94, v94, v95
	v_cvt_pk_bf16_f32 v95, v108, v109
	s_and_saveexec_b64 s[8:9], s[6:7]
	s_cbranch_execz .LBB0_786
	s_waitcnt vmcnt(8)
	v_pk_mul_f32 v[80:81], v[82:83], v[242:243]
	v_pk_mul_f32 v[98:99], v[96:97], v[240:241]
	v_pk_mul_f32 v[242:243], v[90:91], v[242:243]
	v_pk_mul_f32 v[240:241], v[88:89], v[240:241]
	v_pk_fma_f32 v[90:91], v[90:91], v[250:251], v[80:81] neg_lo:[0,0,1] neg_hi:[0,0,1]
	v_pk_fma_f32 v[88:89], v[88:89], v[248:249], v[98:99] neg_lo:[0,0,1] neg_hi:[0,0,1]
	v_pk_fma_f32 v[82:83], v[82:83], v[250:251], v[242:243]
	v_pk_fma_f32 v[96:97], v[96:97], v[248:249], v[240:241]
.LBB0_786:
	s_or_b64 exec, exec, s[8:9]
	s_movk_i32 s100, 0x4800
	v_lshl_add_u64 v[254:255], v[252:253], 0, s[100:101]
	s_mov_b64 exec, s[98:99]
	s_cbranch_execz .Lq_pf_skip2
	global_load_dwordx4 v[240:243], v[254:255], off offset:64
	global_load_dwordx4 v[248:251], v[254:255], off
.Lq_pf_skip2:
	s_mov_b64 exec, -1
	v_add_f32_e32 v80, v144, v145
	v_add_f32_e32 v81, v146, v147
	v_cvt_pk_bf16_f32 v88, v88, v89
	v_cvt_pk_bf16_f32 v89, v90, v91
	v_cvt_pk_bf16_f32 v90, v96, v97
	v_cvt_pk_bf16_f32 v91, v82, v83
	ds_write_b128 v212, v[92:95]
	ds_write_b128 v212, v[88:91] offset:64
	v_add_f32_e32 v80, v80, v81
	v_add_f32_e32 v81, v190, v191
	v_add_f32_e32 v80, v80, v81
	ds_read_b128 v[88:91], v132
	ds_read_b128 v[92:95], v132 offset:1152
	v_fmamk_f32 v80, v80, 0x3b2aaaab, v211
	v_rsq_f32_e32 v80, v80
	v_add_co_u32_e64 v82, s[8:9], s63, v126
	v_mul_f32_e32 v80, 0x3e16c740, v80
	s_nop 0
	v_addc_co_u32_e64 v83, s[8:9], 0, v127, s[8:9]
	s_waitcnt lgkmcnt(1)
	global_store_dwordx4 v[82:83], v[88:91], off
	v_add_co_u32_e64 v82, s[8:9], s67, v126
	v_pk_mul_f32 v[78:79], v[78:79], v[80:81] op_sel_hi:[1,0]
	s_nop 0
	v_addc_co_u32_e64 v83, s[8:9], 0, v127, s[8:9]
	s_waitcnt lgkmcnt(0)
	global_store_dwordx4 v[82:83], v[92:95], off
	v_lshlrev_b64 v[82:83], 7, v[188:189]
	v_pk_mul_f32 v[76:77], v[76:77], v[80:81] op_sel_hi:[1,0]
	v_pk_mul_f32 v[88:89], v[74:75], v[80:81] op_sel_hi:[1,0]
	v_pk_mul_f32 v[74:75], v[72:73], v[80:81] op_sel_hi:[1,0]
	v_lshl_add_u64 v[82:83], s[18:19], 0, v[82:83]
	s_and_saveexec_b64 s[8:9], vcc
	s_cbranch_execz .LBB0_788
	s_waitcnt vmcnt(8)
	v_pk_mul_f32 v[72:73], v[88:89], v[226:227]
	v_pk_mul_f32 v[98:99], v[74:75], v[224:225]
	v_pk_mul_f32 v[226:227], v[78:79], v[226:227]
	v_pk_mul_f32 v[224:225], v[76:77], v[224:225]
	v_pk_fma_f32 v[78:79], v[78:79], v[230:231], v[72:73] neg_lo:[0,0,1] neg_hi:[0,0,1]
	v_pk_fma_f32 v[76:77], v[76:77], v[228:229], v[98:99] neg_lo:[0,0,1] neg_hi:[0,0,1]
	v_pk_fma_f32 v[88:89], v[88:89], v[230:231], v[226:227]
	v_pk_fma_f32 v[74:75], v[74:75], v[228:229], v[224:225]
.LBB0_788:
	s_or_b64 exec, exec, s[8:9]
	v_mov_b32_e32 v81, v80
	v_cvt_pk_bf16_f32 v72, v76, v77
	v_mov_b32_e32 v76, v80
	v_mov_b32_e32 v77, v80
	v_pk_mul_f32 v[70:71], v[70:71], v[76:77]
	v_pk_mul_f32 v[68:69], v[68:69], v[80:81]
	v_pk_mul_f32 v[66:67], v[66:67], v[76:77]
	v_pk_mul_f32 v[76:77], v[64:65], v[80:81]
	v_cvt_pk_bf16_f32 v73, v78, v79
	v_cvt_pk_bf16_f32 v74, v74, v75
	v_cvt_pk_bf16_f32 v75, v88, v89
	s_and_saveexec_b64 s[8:9], s[6:7]
	s_cbranch_execz .LBB0_790
	s_waitcnt vmcnt(8)
	v_pk_mul_f32 v[64:65], v[66:67], v[226:227]
	v_pk_mul_f32 v[82:83], v[76:77], v[224:225]
	v_pk_mul_f32 v[226:227], v[70:71], v[226:227]
	v_pk_mul_f32 v[224:225], v[68:69], v[224:225]
	v_pk_fma_f32 v[70:71], v[70:71], v[230:231], v[64:65] neg_lo:[0,0,1] neg_hi:[0,0,1]
	v_pk_fma_f32 v[68:69], v[68:69], v[228:229], v[82:83] neg_lo:[0,0,1] neg_hi:[0,0,1]
	v_pk_fma_f32 v[66:67], v[66:67], v[230:231], v[226:227]
	v_pk_fma_f32 v[76:77], v[76:77], v[228:229], v[224:225]
.LBB0_790:
	s_or_b64 exec, exec, s[8:9]
	s_movk_i32 s100, 0x5000
	v_lshl_add_u64 v[254:255], v[252:253], 0, s[100:101]
	s_mov_b64 exec, s[98:99]
	s_cbranch_execz .Lq_pf_skip3
	global_load_dwordx4 v[224:227], v[254:255], off offset:64
	global_load_dwordx4 v[228:231], v[254:255], off
.Lq_pf_skip3:
	s_mov_b64 exec, -1
	v_add_f32_e32 v64, v140, v141
	v_add_f32_e32 v65, v142, v143
	v_cvt_pk_bf16_f32 v68, v68, v69
	v_cvt_pk_bf16_f32 v69, v70, v71
	v_cvt_pk_bf16_f32 v70, v76, v77
	v_cvt_pk_bf16_f32 v71, v66, v67
	ds_write_b128 v212, v[72:75]
	ds_write_b128 v212, v[68:71] offset:64
	v_add_f32_e32 v64, v64, v65
	v_add_f32_e32 v65, v186, v187
	v_add_f32_e32 v64, v64, v65
	ds_read_b128 v[66:69], v132
	ds_read_b128 v[70:73], v132 offset:1152
	v_fmamk_f32 v64, v64, 0x3b2aaaab, v211
	v_rsq_f32_e32 v64, v64
	v_add_co_u32_e64 v74, s[8:9], s48, v126
	v_mul_f32_e32 v64, 0x3e16c740, v64
	s_nop 0
	v_addc_co_u32_e64 v75, s[8:9], 0, v127, s[8:9]
	s_waitcnt lgkmcnt(1)
	global_store_dwordx4 v[74:75], v[66:69], off
	v_pk_mul_f32 v[62:63], v[62:63], v[64:65] op_sel_hi:[1,0]
	v_pk_mul_f32 v[60:61], v[60:61], v[64:65] op_sel_hi:[1,0]
	v_add_co_u32_e64 v66, s[8:9], s68, v126
	v_pk_mul_f32 v[68:69], v[58:59], v[64:65] op_sel_hi:[1,0]
	s_nop 0
	v_addc_co_u32_e64 v67, s[8:9], 0, v127, s[8:9]
	s_waitcnt lgkmcnt(0)
	global_store_dwordx4 v[66:67], v[70:73], off
	v_lshlrev_b64 v[66:67], 7, v[184:185]
	v_pk_mul_f32 v[58:59], v[56:57], v[64:65] op_sel_hi:[1,0]
	v_lshl_add_u64 v[66:67], s[18:19], 0, v[66:67]
	s_and_saveexec_b64 s[8:9], vcc
	s_cbranch_execz .LBB0_792
	s_waitcnt vmcnt(8)
	v_pk_mul_f32 v[56:57], v[68:69], v[234:235]
	v_pk_mul_f32 v[78:79], v[58:59], v[232:233]
	v_pk_mul_f32 v[234:235], v[62:63], v[234:235]
	v_pk_mul_f32 v[232:233], v[60:61], v[232:233]
	v_pk_fma_f32 v[62:63], v[62:63], v[238:239], v[56:57] neg_lo:[0,0,1] neg_hi:[0,0,1]
	v_pk_fma_f32 v[60:61], v[60:61], v[236:237], v[78:79] neg_lo:[0,0,1] neg_hi:[0,0,1]
	v_pk_fma_f32 v[68:69], v[68:69], v[238:239], v[234:235]
	v_pk_fma_f32 v[58:59], v[58:59], v[236:237], v[232:233]
.LBB0_792:
	s_or_b64 exec, exec, s[8:9]
	v_mov_b32_e32 v65, v64
	v_cvt_pk_bf16_f32 v56, v60, v61
	v_mov_b32_e32 v60, v64
	v_mov_b32_e32 v61, v64
	v_pk_mul_f32 v[54:55], v[54:55], v[60:61]
	v_pk_mul_f32 v[52:53], v[52:53], v[64:65]
	v_pk_mul_f32 v[50:51], v[50:51], v[60:61]
	v_pk_mul_f32 v[60:61], v[48:49], v[64:65]
	v_cvt_pk_bf16_f32 v57, v62, v63
	v_cvt_pk_bf16_f32 v58, v58, v59
	v_cvt_pk_bf16_f32 v59, v68, v69
	s_and_saveexec_b64 s[8:9], s[6:7]
	s_cbranch_execz .LBB0_794
	s_waitcnt vmcnt(8)
	v_pk_mul_f32 v[48:49], v[50:51], v[234:235]
	v_pk_mul_f32 v[70:71], v[60:61], v[232:233]
	v_pk_mul_f32 v[234:235], v[54:55], v[234:235]
	v_pk_mul_f32 v[232:233], v[52:53], v[232:233]
	v_pk_fma_f32 v[54:55], v[54:55], v[238:239], v[48:49] neg_lo:[0,0,1] neg_hi:[0,0,1]
	v_pk_fma_f32 v[52:53], v[52:53], v[236:237], v[70:71] neg_lo:[0,0,1] neg_hi:[0,0,1]
	v_pk_fma_f32 v[50:51], v[50:51], v[238:239], v[234:235]
	v_pk_fma_f32 v[60:61], v[60:61], v[236:237], v[232:233]
.LBB0_794:
	s_or_b64 exec, exec, s[8:9]
	s_movk_i32 s100, 0x5800
	v_lshl_add_u64 v[254:255], v[252:253], 0, s[100:101]
	s_mov_b64 exec, s[98:99]
	s_cbranch_execz .Lq_pf_skip4
	global_load_dwordx4 v[232:235], v[254:255], off offset:64
	global_load_dwordx4 v[236:239], v[254:255], off
.Lq_pf_skip4:
	s_mov_b64 exec, -1
	v_add_f32_e32 v48, v120, v121
	v_add_f32_e32 v49, v122, v123
	v_cvt_pk_bf16_f32 v52, v52, v53
	v_cvt_pk_bf16_f32 v53, v54, v55
	v_cvt_pk_bf16_f32 v54, v60, v61
	v_cvt_pk_bf16_f32 v55, v50, v51
	ds_write_b128 v212, v[56:59]
	ds_write_b128 v212, v[52:55] offset:64
	v_add_f32_e32 v48, v48, v49
	v_add_f32_e32 v49, v182, v183
	v_add_f32_e32 v48, v48, v49
	ds_read_b128 v[50:53], v132
	ds_read_b128 v[54:57], v132 offset:1152
	v_fmamk_f32 v48, v48, 0x3b2aaaab, v211
	v_rsq_f32_e32 v48, v48
	v_add_co_u32_e64 v58, s[8:9], s46, v126
	v_mul_f32_e32 v48, 0x3e16c740, v48
	s_nop 0
	v_addc_co_u32_e64 v59, s[8:9], 0, v127, s[8:9]
	s_waitcnt lgkmcnt(1)
	global_store_dwordx4 v[58:59], v[50:53], off
	v_pk_mul_f32 v[46:47], v[46:47], v[48:49] op_sel_hi:[1,0]
	v_pk_mul_f32 v[44:45], v[44:45], v[48:49] op_sel_hi:[1,0]
	v_add_co_u32_e64 v50, s[8:9], s69, v126
	v_pk_mul_f32 v[52:53], v[42:43], v[48:49] op_sel_hi:[1,0]
	s_nop 0
	v_addc_co_u32_e64 v51, s[8:9], 0, v127, s[8:9]
	s_waitcnt lgkmcnt(0)
	global_store_dwordx4 v[50:51], v[54:57], off
	v_lshlrev_b64 v[50:51], 7, v[180:181]
	v_pk_mul_f32 v[42:43], v[40:41], v[48:49] op_sel_hi:[1,0]
	v_lshl_add_u64 v[50:51], s[18:19], 0, v[50:51]
	s_and_saveexec_b64 s[8:9], vcc
	s_cbranch_execz .LBB0_796
	s_waitcnt vmcnt(8)
	v_pk_mul_f32 v[40:41], v[52:53], v[242:243]
	v_pk_mul_f32 v[62:63], v[42:43], v[240:241]
	v_pk_mul_f32 v[242:243], v[46:47], v[242:243]
	v_pk_mul_f32 v[240:241], v[44:45], v[240:241]
	v_pk_fma_f32 v[46:47], v[46:47], v[250:251], v[40:41] neg_lo:[0,0,1] neg_hi:[0,0,1]
	v_pk_fma_f32 v[44:45], v[44:45], v[248:249], v[62:63] neg_lo:[0,0,1] neg_hi:[0,0,1]
	v_pk_fma_f32 v[52:53], v[52:53], v[250:251], v[242:243]
	v_pk_fma_f32 v[42:43], v[42:43], v[248:249], v[240:241]
.LBB0_796:
	s_or_b64 exec, exec, s[8:9]
	v_mov_b32_e32 v49, v48
	v_cvt_pk_bf16_f32 v40, v44, v45
	v_mov_b32_e32 v44, v48
	v_mov_b32_e32 v45, v48
	v_pk_mul_f32 v[38:39], v[38:39], v[44:45]
	v_pk_mul_f32 v[36:37], v[36:37], v[48:49]
	v_pk_mul_f32 v[34:35], v[34:35], v[44:45]
	v_pk_mul_f32 v[44:45], v[32:33], v[48:49]
	v_cvt_pk_bf16_f32 v41, v46, v47
	v_cvt_pk_bf16_f32 v42, v42, v43
	v_cvt_pk_bf16_f32 v43, v52, v53
	s_and_saveexec_b64 s[8:9], s[6:7]
	s_cbranch_execz .LBB0_798
	s_waitcnt vmcnt(8)
	v_pk_mul_f32 v[32:33], v[34:35], v[242:243]
	v_pk_mul_f32 v[54:55], v[44:45], v[240:241]
	v_pk_mul_f32 v[242:243], v[38:39], v[242:243]
	v_pk_mul_f32 v[240:241], v[36:37], v[240:241]
	v_pk_fma_f32 v[38:39], v[38:39], v[250:251], v[32:33] neg_lo:[0,0,1] neg_hi:[0,0,1]
	v_pk_fma_f32 v[36:37], v[36:37], v[248:249], v[54:55] neg_lo:[0,0,1] neg_hi:[0,0,1]
	v_pk_fma_f32 v[34:35], v[34:35], v[250:251], v[242:243]
	v_pk_fma_f32 v[44:45], v[44:45], v[248:249], v[240:241]
.LBB0_798:
	s_or_b64 exec, exec, s[8:9]
	v_add_f32_e32 v32, v100, v101
	v_add_f32_e32 v33, v102, v103
	v_cvt_pk_bf16_f32 v36, v36, v37
	v_cvt_pk_bf16_f32 v37, v38, v39
	v_cvt_pk_bf16_f32 v38, v44, v45
	v_cvt_pk_bf16_f32 v39, v34, v35
	ds_write_b128 v212, v[40:43]
	ds_write_b128 v212, v[36:39] offset:64
	v_add_f32_e32 v32, v32, v33
	v_add_f32_e32 v33, v178, v179
	v_add_f32_e32 v32, v32, v33
	ds_read_b128 v[34:37], v132
	ds_read_b128 v[38:41], v132 offset:1152
	v_fmamk_f32 v32, v32, 0x3b2aaaab, v211
	v_rsq_f32_e32 v32, v32
	v_add_co_u32_e64 v42, s[8:9], s70, v126
	v_mul_f32_e32 v32, 0x3e16c740, v32
	s_nop 0
	v_addc_co_u32_e64 v43, s[8:9], 0, v127, s[8:9]
	s_waitcnt lgkmcnt(1)
	global_store_dwordx4 v[42:43], v[34:37], off
	v_pk_mul_f32 v[30:31], v[30:31], v[32:33] op_sel_hi:[1,0]
	v_pk_mul_f32 v[28:29], v[28:29], v[32:33] op_sel_hi:[1,0]
	v_add_co_u32_e64 v34, s[8:9], s71, v126
	v_pk_mul_f32 v[36:37], v[26:27], v[32:33] op_sel_hi:[1,0]
	s_nop 0
	v_addc_co_u32_e64 v35, s[8:9], 0, v127, s[8:9]
	s_waitcnt lgkmcnt(0)
	global_store_dwordx4 v[34:35], v[38:41], off
	v_lshlrev_b64 v[34:35], 7, v[176:177]
	v_pk_mul_f32 v[26:27], v[24:25], v[32:33] op_sel_hi:[1,0]
	v_lshl_add_u64 v[34:35], s[18:19], 0, v[34:35]
	s_and_saveexec_b64 s[8:9], vcc
	s_cbranch_execz .LBB0_800
	s_waitcnt vmcnt(6)
	v_pk_mul_f32 v[24:25], v[36:37], v[226:227]
	v_pk_mul_f32 v[46:47], v[26:27], v[224:225]
	v_pk_mul_f32 v[226:227], v[30:31], v[226:227]
	v_pk_mul_f32 v[224:225], v[28:29], v[224:225]
	v_pk_fma_f32 v[30:31], v[30:31], v[230:231], v[24:25] neg_lo:[0,0,1] neg_hi:[0,0,1]
	v_pk_fma_f32 v[28:29], v[28:29], v[228:229], v[46:47] neg_lo:[0,0,1] neg_hi:[0,0,1]
	v_pk_fma_f32 v[36:37], v[36:37], v[230:231], v[226:227]
	v_pk_fma_f32 v[26:27], v[26:27], v[228:229], v[224:225]
.LBB0_800:
	s_or_b64 exec, exec, s[8:9]
	v_mov_b32_e32 v33, v32
	v_cvt_pk_bf16_f32 v24, v28, v29
	v_mov_b32_e32 v28, v32
	v_mov_b32_e32 v29, v32
	v_pk_mul_f32 v[22:23], v[22:23], v[28:29]
	v_pk_mul_f32 v[20:21], v[20:21], v[32:33]
	v_pk_mul_f32 v[18:19], v[18:19], v[28:29]
	v_pk_mul_f32 v[28:29], v[16:17], v[32:33]
	v_cvt_pk_bf16_f32 v25, v30, v31
	v_cvt_pk_bf16_f32 v26, v26, v27
	v_cvt_pk_bf16_f32 v27, v36, v37
	s_and_saveexec_b64 s[8:9], s[6:7]
	s_cbranch_execz .LBB0_802
	s_waitcnt vmcnt(6)
	v_pk_mul_f32 v[16:17], v[18:19], v[226:227]
	v_pk_mul_f32 v[38:39], v[28:29], v[224:225]
	v_pk_mul_f32 v[226:227], v[22:23], v[226:227]
	v_pk_mul_f32 v[224:225], v[20:21], v[224:225]
	v_pk_fma_f32 v[22:23], v[22:23], v[230:231], v[16:17] neg_lo:[0,0,1] neg_hi:[0,0,1]
	v_pk_fma_f32 v[20:21], v[20:21], v[228:229], v[38:39] neg_lo:[0,0,1] neg_hi:[0,0,1]
	v_pk_fma_f32 v[18:19], v[18:19], v[230:231], v[226:227]
	v_pk_fma_f32 v[28:29], v[28:29], v[228:229], v[224:225]
.LBB0_802:
	s_or_b64 exec, exec, s[8:9]
	v_add_f32_e32 v16, v84, v85
	v_add_f32_e32 v17, v86, v87
	v_cvt_pk_bf16_f32 v20, v20, v21
	v_cvt_pk_bf16_f32 v21, v22, v23
	v_cvt_pk_bf16_f32 v22, v28, v29
	v_cvt_pk_bf16_f32 v23, v18, v19
	ds_write_b128 v212, v[24:27]
	ds_write_b128 v212, v[20:23] offset:64
	v_add_f32_e32 v16, v16, v17
	v_add_f32_e32 v17, v174, v175
	v_add_f32_e32 v16, v16, v17
	ds_read_b128 v[18:21], v132
	ds_read_b128 v[22:25], v132 offset:1152
	v_fmamk_f32 v16, v16, 0x3b2aaaab, v211
	v_rsq_f32_e32 v16, v16
	v_add_co_u32_e64 v26, s[8:9], s72, v126
	v_mul_f32_e32 v16, 0x3e16c740, v16
	s_nop 0
	v_addc_co_u32_e64 v27, s[8:9], 0, v127, s[8:9]
	s_waitcnt lgkmcnt(1)
	global_store_dwordx4 v[26:27], v[18:21], off
	v_pk_mul_f32 v[14:15], v[14:15], v[16:17] op_sel_hi:[1,0]
	v_pk_mul_f32 v[12:13], v[12:13], v[16:17] op_sel_hi:[1,0]
	v_add_co_u32_e64 v18, s[8:9], s73, v126
	v_pk_mul_f32 v[20:21], v[10:11], v[16:17] op_sel_hi:[1,0]
	s_nop 0
	v_addc_co_u32_e64 v19, s[8:9], 0, v127, s[8:9]
	s_waitcnt lgkmcnt(0)
	global_store_dwordx4 v[18:19], v[22:25], off
	v_lshlrev_b64 v[18:19], 7, v[170:171]
	v_pk_mul_f32 v[10:11], v[8:9], v[16:17] op_sel_hi:[1,0]
	v_lshl_add_u64 v[18:19], s[18:19], 0, v[18:19]
	s_and_saveexec_b64 s[8:9], vcc
	s_cbranch_execz .LBB0_804
	s_waitcnt vmcnt(4)
	v_pk_mul_f32 v[8:9], v[20:21], v[234:235]
	v_pk_mul_f32 v[30:31], v[10:11], v[232:233]
	v_pk_mul_f32 v[234:235], v[14:15], v[234:235]
	v_pk_mul_f32 v[232:233], v[12:13], v[232:233]
	v_pk_fma_f32 v[14:15], v[14:15], v[238:239], v[8:9] neg_lo:[0,0,1] neg_hi:[0,0,1]
	v_pk_fma_f32 v[12:13], v[12:13], v[236:237], v[30:31] neg_lo:[0,0,1] neg_hi:[0,0,1]
	v_pk_fma_f32 v[20:21], v[20:21], v[238:239], v[234:235]
	v_pk_fma_f32 v[10:11], v[10:11], v[236:237], v[232:233]
.LBB0_804:
	s_or_b64 exec, exec, s[8:9]
	v_mov_b32_e32 v17, v16
	v_cvt_pk_bf16_f32 v8, v12, v13
	v_mov_b32_e32 v12, v16
	v_mov_b32_e32 v13, v16
	v_pk_mul_f32 v[6:7], v[6:7], v[12:13]
	v_pk_mul_f32 v[4:5], v[4:5], v[16:17]
	v_pk_mul_f32 v[2:3], v[2:3], v[12:13]
	v_pk_mul_f32 v[0:1], v[0:1], v[16:17]
	v_cvt_pk_bf16_f32 v9, v14, v15
	v_cvt_pk_bf16_f32 v10, v10, v11
	v_cvt_pk_bf16_f32 v11, v20, v21
	s_and_saveexec_b64 s[8:9], s[6:7]
	s_cbranch_execz .LBB0_806
	s_waitcnt vmcnt(4)
	v_pk_mul_f32 v[20:21], v[2:3], v[234:235]
	v_pk_mul_f32 v[22:23], v[0:1], v[232:233]
	v_pk_mul_f32 v[234:235], v[6:7], v[234:235]
	v_pk_mul_f32 v[232:233], v[4:5], v[232:233]
	v_pk_fma_f32 v[6:7], v[6:7], v[238:239], v[20:21] neg_lo:[0,0,1] neg_hi:[0,0,1]
	v_pk_fma_f32 v[4:5], v[4:5], v[236:237], v[22:23] neg_lo:[0,0,1] neg_hi:[0,0,1]
	v_pk_fma_f32 v[2:3], v[2:3], v[238:239], v[234:235]
	v_pk_fma_f32 v[0:1], v[0:1], v[236:237], v[232:233]

	.amdhsa_kernel _Z8yoco_fwd4Args
		.amdhsa_group_segment_fixed_size 0
		.amdhsa_private_segment_fixed_size 0
		.amdhsa_kernarg_size 416
		.amdhsa_user_sgpr_count 2
		.amdhsa_user_sgpr_dispatch_ptr 0
		.amdhsa_user_sgpr_queue_ptr 0
		.amdhsa_user_sgpr_kernarg_segment_ptr 1
		.amdhsa_user_sgpr_dispatch_id 0
		.amdhsa_user_sgpr_kernarg_preload_length 0
		.amdhsa_user_sgpr_kernarg_preload_offset 0
		.amdhsa_user_sgpr_private_segment_size 0
		.amdhsa_uses_dynamic_stack 0
		.amdhsa_enable_private_segment 0
		.amdhsa_system_sgpr_workgroup_id_x 1
		.amdhsa_system_sgpr_workgroup_id_y 0
		.amdhsa_system_sgpr_workgroup_id_z 0
		.amdhsa_system_sgpr_workgroup_info 0
		.amdhsa_system_vgpr_workitem_id 0
		.amdhsa_next_free_vgpr 256
		.amdhsa_next_free_sgpr 102
		.amdhsa_accum_offset 256
		.amdhsa_reserve_vcc 1
		.amdhsa_float_round_mode_32 0
		.amdhsa_float_round_mode_16_64 0
		.amdhsa_float_denorm_mode_32 3
		.amdhsa_float_denorm_mode_16_64 3
		.amdhsa_dx10_clamp 1
		.amdhsa_ieee_mode 1
		.amdhsa_fp16_overflow 0
		.amdhsa_tg_split 0
		.amdhsa_exception_fp_ieee_invalid_op 0
		.amdhsa_exception_fp_denorm_src 0
		.amdhsa_exception_fp_ieee_div_zero 0
		.amdhsa_exception_fp_ieee_overflow 0
		.amdhsa_exception_fp_ieee_underflow 0
		.amdhsa_exception_fp_ieee_inexact 0
		.amdhsa_exception_int_div_zero 0
	.end_amdhsa_kernel

amdhsa.kernels:
  - .agpr_count:     0
    .args:
      - .offset:         0
        .size:           160
        .value_kind:     by_value
      - .offset:         160
        .size:           4
        .value_kind:     hidden_block_count_x
      - .offset:         164
        .size:           4
        .value_kind:     hidden_block_count_y
      - .offset:         168
        .size:           4
        .value_kind:     hidden_block_count_z
      - .offset:         172
        .size:           2
        .value_kind:     hidden_group_size_x
      - .offset:         174
        .size:           2
        .value_kind:     hidden_group_size_y
      - .offset:         176
        .size:           2
        .value_kind:     hidden_group_size_z
      - .offset:         178
        .size:           2
        .value_kind:     hidden_remainder_x
      - .offset:         180
        .size:           2
        .value_kind:     hidden_remainder_y
      - .offset:         182
        .size:           2
        .value_kind:     hidden_remainder_z
      - .offset:         200
        .size:           8
        .value_kind:     hidden_global_offset_x
      - .offset:         208
        .size:           8
        .value_kind:     hidden_global_offset_y
      - .offset:         216
        .size:           8
        .value_kind:     hidden_global_offset_z
      - .offset:         224
        .size:           2
        .value_kind:     hidden_grid_dims
      - .offset:         280
        .size:           4
        .value_kind:     hidden_dynamic_lds_size
    .group_segment_fixed_size: 0
    .kernarg_segment_align: 8
    .kernarg_segment_size: 416
    .language:       OpenCL C
    .language_version:
      - 2
      - 0
    .max_flat_workgroup_size: 512
    .name:           _Z8yoco_fwd4Args
    .private_segment_fixed_size: 0
    .sgpr_count:     108
    .sgpr_spill_count: 29
    .symbol:         _Z8yoco_fwd4Args.kd
    .uniform_work_group_size: 1
    .uses_dynamic_stack: false
    .vgpr_count:     256
    .vgpr_spill_count: 0
    .wavefront_size: 64
